# K-loop back edge rotated: counter / pointer / exit-test SALU moved in front of the loop-back barrier (only the branch stays behind it); on top of K1
# baseline (speedup 1.0000x reference)
; #define PG8_MMA(ai, bj, At, Bt) do { __builtin_amdgcn_s_setprio(1); _Pragma("unroll") for (int m = 0; m < 4; ++m) _Pragma("unroll") for (int n = 0; n < 2; ++n) _Pragma("unroll") for (int k = 0; k < 2; ++k) \
;         acc[ai][bj][m][n] = __builtin_amdgcn_mfma_f32_16x16x32_bf16(Bt[n][k], At[m][k], acc[ai][bj][m][n], 0, 0, 0); __builtin_amdgcn_s_setprio(0); } while (0)
; #define PG8_WAIT_V(n) asm volatile("s_waitcnt vmcnt(" #n ")" ::: "memory")
; #define PG8_WAIT_L(n) asm volatile("s_waitcnt lgkmcnt(" #n ")" ::: "memory")
; #define PG8_BAR __builtin_amdgcn_s_barrier()
; #define PG8_SCHED __builtin_amdgcn_sched_barrier(0)
; __device__ __forceinline__ void gemm_phase(LAS unsigned char* lds, const Call& C, const int tid, const Args& args) {
;     ...
;             PG8_WAIT_V(8); PG8_WAIT_L(0); PG8_BAR; PG8_MMA(1, 0, At, B0); PG8_MMA(1, 1, At, B1); PG8_BAR; PG8_SCHED;
;         }
.Lk1_over:
	s_waitcnt vmcnt(8)
	s_waitcnt lgkmcnt(0)
	s_barrier
	s_setprio 1
	s_waitcnt lgkmcnt(0)
	v_mfma_f32_16x16x32_bf16 v[64:67], v[136:139], v[168:171], v[64:67]
	v_mfma_f32_16x16x32_bf16 v[56:59], v[144:147], v[168:171], v[56:59]
	v_mfma_f32_16x16x32_bf16 v[52:55], v[136:139], v[176:179], v[52:55]
	v_mfma_f32_16x16x32_bf16 v[48:51], v[144:147], v[176:179], v[48:51]
	v_mfma_f32_16x16x32_bf16 v[36:39], v[136:139], v[184:187], v[36:39]
	v_mfma_f32_16x16x32_bf16 v[32:35], v[144:147], v[184:187], v[32:35]
	v_mfma_f32_16x16x32_bf16 v[20:23], v[136:139], v[192:195], v[20:23]
	v_mfma_f32_16x16x32_bf16 v[16:19], v[144:147], v[192:195], v[16:19]
	v_mfma_f32_16x16x32_bf16 v[64:67], v[140:143], v[172:175], v[64:67]
	v_mfma_f32_16x16x32_bf16 v[56:59], v[148:151], v[172:175], v[56:59]
	v_mfma_f32_16x16x32_bf16 v[52:55], v[140:143], v[180:183], v[52:55]
	v_mfma_f32_16x16x32_bf16 v[48:51], v[148:151], v[180:183], v[48:51]
	v_mfma_f32_16x16x32_bf16 v[36:39], v[140:143], v[188:191], v[36:39]
	v_mfma_f32_16x16x32_bf16 v[32:35], v[148:151], v[188:191], v[32:35]
	v_mfma_f32_16x16x32_bf16 v[20:23], v[140:143], v[196:199], v[20:23]
	v_mfma_f32_16x16x32_bf16 v[16:19], v[148:151], v[196:199], v[16:19]
	s_setprio 0
	s_setprio 1
	v_mfma_f32_16x16x32_bf16 v[44:47], v[152:155], v[168:171], v[44:47]
	v_mfma_f32_16x16x32_bf16 v[40:43], v[160:163], v[168:171], v[40:43]
	v_mfma_f32_16x16x32_bf16 v[28:31], v[152:155], v[176:179], v[28:31]
	v_mfma_f32_16x16x32_bf16 v[24:27], v[160:163], v[176:179], v[24:27]
	v_mfma_f32_16x16x32_bf16 v[12:15], v[152:155], v[184:187], v[12:15]
	v_mfma_f32_16x16x32_bf16 v[8:11], v[160:163], v[184:187], v[8:11]
	v_mfma_f32_16x16x32_bf16 v[4:7], v[152:155], v[192:195], v[4:7]
	v_mfma_f32_16x16x32_bf16 v[0:3], v[160:163], v[192:195], v[0:3]
	v_mfma_f32_16x16x32_bf16 v[44:47], v[156:159], v[172:175], v[44:47]
	v_mfma_f32_16x16x32_bf16 v[40:43], v[164:167], v[172:175], v[40:43]
	v_mfma_f32_16x16x32_bf16 v[28:31], v[156:159], v[180:183], v[28:31]
	v_mfma_f32_16x16x32_bf16 v[24:27], v[164:167], v[180:183], v[24:27]
	v_mfma_f32_16x16x32_bf16 v[12:15], v[156:159], v[188:191], v[12:15]
	v_mfma_f32_16x16x32_bf16 v[8:11], v[164:167], v[188:191], v[8:11]
	v_mfma_f32_16x16x32_bf16 v[4:7], v[156:159], v[196:199], v[4:7]
	v_mfma_f32_16x16x32_bf16 v[0:3], v[164:167], v[196:199], v[0:3]
	s_setprio 0
	s_add_u32 s16, s16, 0x100
	s_addc_u32 s17, s17, 0
	s_mov_b64 s[0:1], s[8:9]
	s_mov_b32 s24, s25
	s_cmp_ge_u32 s25, s12
	s_barrier
	s_cbranch_scc0 .LBB0_282
	s_and_b64 vcc, exec, s[80:81]
	s_cbranch_vccz .LBB0_285
